# v110 + C pair items: per-head sink load issued at item start before the K/V loads, no load waited on after the item barrier
# speedup vs baseline: 1.0090x; 1.0064x over previous
.LBB0_137:
	s_ashr_i32 s2, s35, 5
	s_and_b32 s13, s2, -2
	s_sub_i32 s2, 28, s13
	s_and_b32 s3, s35, 3
	s_max_i32 s20, s2, 0
	s_lshl_b32 s2, s35, 9
	s_sub_i32 s23, 32, s13
	s_and_b32 s2, s2, 0x7800
	s_lshl_b32 s70, s3, 7
	s_lshl_b32 s6, s3, 2
	v_readlane_b32 s18, v251, 50
	s_add_i32 s6, s6, s29
	v_readlane_b32 s19, v251, 51
	s_ashr_i32 s7, s6, 31
	s_lshl_b64 s[16:17], s[6:7], 2
	s_add_u32 s16, s18, s16
	s_addc_u32 s17, s19, s17
	global_load_dword v206, v1, s[16:17]
	s_cmp_lt_i32 s20, s23
	v_add_u32_e32 v0, s2, v130
	v_lshl_add_u64 v[28:29], v[156:157], 0, s[70:71]
	s_cselect_b64 s[6:7], -1, 0
	s_cmp_ge_i32 s20, s23
	s_cbranch_scc1 .LBB0_139
	v_lshl_add_u32 v2, s20, 6, v0
	v_mad_i64_i32 v[6:7], s[16:17], v2, s95, v[28:29]
	global_load_dwordx4 v[2:5], v[6:7], off offset:2048
	s_nop 0
	global_load_dwordx4 v[6:9], v[6:7], off offset:2560

.LBB0_157:
	s_lshl_b32 s3, s3, 2
	s_add_i32 s6, s3, s29
	s_ashr_i32 s7, s6, 31
	v_readlane_b32 s48, v251, 36
	s_lshl_b64 s[16:17], s[6:7], 2
	v_readlane_b32 s62, v251, 50
	v_readlane_b32 s63, v251, 51
	s_add_u32 s16, s62, s16
	s_waitcnt lgkmcnt(0)
	s_barrier
	s_addc_u32 s17, s63, s17
	v_readlane_b32 s0, v250, 33
	s_or_b32 s12, s2, s0
	s_lshl_b32 s2, s6, 6
	s_ashr_i32 s3, s2, 31
	s_lshl_b64 s[2:3], s[2:3], 1
	v_lshl_add_u64 v[112:113], v[154:155], 0, s[2:3]
	v_lshl_add_u64 v[114:115], v[158:159], 0, s[2:3]
	s_mov_b32 s2, 0
	s_mov_b64 s[16:17], -1
	v_readlane_b32 s49, v251, 37
	v_readlane_b32 s50, v251, 38
	v_readlane_b32 s51, v251, 39
	v_readlane_b32 s52, v251, 40
	v_readlane_b32 s53, v251, 41
	v_readlane_b32 s54, v251, 42
	v_readlane_b32 s55, v251, 43
	v_readlane_b32 s56, v251, 44
	v_readlane_b32 s57, v251, 45
	v_readlane_b32 s58, v251, 46
	v_readlane_b32 s59, v251, 47
	v_readlane_b32 s60, v251, 48
	v_readlane_b32 s61, v251, 49
	s_waitcnt vmcnt(0)
	v_mul_f32_e32 v116, 0x3fb8aa3b, v206
	s_branch .LBB0_160
